# baseline (speedup 1.0000x reference)
; #define LAS __attribute__((address_space(3)))
; __global__ void __launch_bounds__(512, 2) mega_kernel(Params p) {
;   __shared__ __attribute__((aligned(16))) char smem[2 * SMEM_BYTES + 16];
;   __shared__ uint4 xb_words;
;   if (threadIdx.x == 0) xb_words = make_uint4(0u, 0u, 0u, 0u);
;   __syncthreads();
;   const XcdBarrier xb = xcd_barrier_post(p.bar, (volatile LAS unsigned*)&xb_words, (unsigned)(p.nblk >> 1));
_Z11mega_kernel6Params:
	s_mov_b32 s101, 0
	s_load_dwordx4 s[4:7], s[0:1], 0x140
	v_and_b32_e32 v252, 0x3ff, v0
	v_writelane_b32 v253, s2, 0
	s_waitcnt lgkmcnt(0)
	v_writelane_b32 v253, s4, 1
	s_nop 1
	v_writelane_b32 v253, s5, 2
	v_writelane_b32 v253, s6, 3
	v_writelane_b32 v253, s7, 4
	v_cmp_eq_u32_e64 s[4:5], 0, v252
	s_mov_b64 s[2:3], exec
	s_nop 0
	v_writelane_b32 v253, s4, 5
	s_nop 1
	v_writelane_b32 v253, s5, 6
	s_and_b64 s[4:5], s[2:3], s[4:5]
	s_mov_b64 exec, s[4:5]
	s_cbranch_execz .LBB0_2
	v_mov_b32_e32 v2, 0
	v_mov_b32_e32 v3, v2
	v_mov_b32_e32 v4, v2
	v_mov_b32_e32 v5, v2
	v_mov_b32_e32 v1, 0x26010
	ds_write_b128 v1, v[2:5]

; __device__ __forceinline__ int tid_op() { int t = threadIdx.x & 255; asm volatile("" : "+v"(t)); return t; }
; __device__ __forceinline__ int vb_op() { return (int)(blockIdx.x << 1) | sub_op(); }
; __device__ void rms_row(const float* __restrict__ src, const float* __restrict__ gain, u16* __restrict__ dst, int row) {
;   const int lane = tid_op() & 63;
;   const float4* s4 = (const float4*)(src + (size_t)row * DM);
;   float4 v[8];
;   float ss = 0.f;
; #pragma unroll
;   for (int i = 0; i < 8; ++i) {
;     v[i] = s4[i * 64 + lane];
;     ss += v[i].x * v[i].x + v[i].y * v[i].y + v[i].z * v[i].z + v[i].w * v[i].w;
;   }
; __device__ void phase0(const Params& p, char* smem) {
;     ...
;   for (int u = vb_op(); u < U6; u += p.nblk) {
;     if (u < U0) {
;       rms_row(p.x, p.attn_norm, p.xn, u * 4 + wv);
.LBB0_58:
	s_andn2_b64 vcc, exec, s[4:5]
	s_cbranch_vccnz .LBB0_7
	s_cmp_eq_u32 s101, 0
	s_cbranch_scc1 .Lrms_go
	s_sub_i32 s101, s101, 1
	s_branch .LBB0_7
.Lrms_go:
	s_lshr_b32 s98, s9, 2
	s_add_i32 s98, s98, s8
	s_cmp_lt_i32 s98, 0x2000
	s_cbranch_scc0 .Lrms_single
	s_mov_b32 s101, 1
	v_mov_b32_e32 v3, v167
	v_add_u32_e32 v2, 0x11000, v66
	s_load_dwordx16 s[52:67], s[0:1], 0x0
	v_and_b32_e32 v10, 63, v3
	v_ashrrev_i32_e32 v3, 31, v2
	v_cmp_lt_i32_e32 vcc, v94, v93
	v_lshlrev_b64 v[4:5], 13, v[2:3]
	s_load_dwordx16 s[36:51], s[0:1], 0x80
	v_cndmask_b32_e32 v3, v92, v94, vcc
	v_cmp_lt_i32_e32 vcc, v95, v93
	v_lshlrev_b32_e32 v112, 2, v3
	v_lshlrev_b32_e32 v68, 4, v10
	v_cndmask_b32_e32 v3, v92, v95, vcc
	v_cmp_lt_i32_e32 vcc, v96, v93
	v_lshlrev_b32_e32 v103, 2, v3
	s_waitcnt lgkmcnt(0)
	v_lshl_add_u64 v[4:5], s[52:53], 0, v[4:5]
	v_cndmask_b32_e32 v3, v92, v96, vcc
	v_cmp_lt_i32_e32 vcc, v97, v93
	v_lshlrev_b32_e32 v102, 2, v3
	v_or_b32_e32 v38, 0x1000, v68
	v_cndmask_b32_e32 v3, v92, v97, vcc
	v_cmp_lt_i32_e32 vcc, v98, v93
	v_mov_b32_e32 v39, v69
	v_or_b32_e32 v46, 0x1400, v68
	v_mov_b32_e32 v47, v69
	v_or_b32_e32 v54, 0x1800, v68
	v_mov_b32_e32 v55, v69
	v_or_b32_e32 v62, 0x1c00, v68
	v_mov_b32_e32 v63, v69
	v_lshlrev_b32_e32 v101, 2, v3
	v_cndmask_b32_e32 v3, v92, v98, vcc
	v_cmp_lt_i32_e32 vcc, v99, v93
	v_lshl_add_u64 v[26:27], v[4:5], 0, v[68:69]
	v_lshl_add_u64 v[34:35], v[4:5], 0, v[38:39]
	v_lshl_add_u64 v[42:43], v[4:5], 0, v[46:47]
	v_lshl_add_u64 v[50:51], v[4:5], 0, v[54:55]
	v_lshl_add_u64 v[58:59], v[4:5], 0, v[62:63]
	v_lshlrev_b32_e32 v100, 2, v3
	v_cndmask_b32_e32 v3, v92, v99, vcc
	v_mov_b64_e32 v[4:5], s[42:43]
	v_lshlrev_b32_e32 v67, 2, v3
	v_mad_i64_i32 v[2:3], s[4:5], v2, s16, v[4:5]
	v_lshlrev_b32_e32 v4, 3, v10
	v_mov_b32_e32 v5, v69
	global_load_dwordx4 v[6:9], v[26:27], off
	global_load_dwordx4 v[22:25], v[26:27], off offset:1024
	global_load_dwordx4 v[14:17], v68, s[54:55]
	global_load_dwordx4 v[18:21], v68, s[54:55] offset:1024
	v_lshl_add_u64 v[70:71], v[2:3], 0, v[4:5]
	global_load_dwordx4 v[2:5], v[26:27], off offset:2048
	global_load_dwordx4 v[10:13], v68, s[54:55] offset:2048
	global_load_dwordx4 v[30:33], v68, s[54:55] offset:3072
	s_mov_b32 s4, 0x800000
	global_load_dwordx4 v[26:29], v[26:27], off offset:3072
	s_nop 0
	global_load_dwordx4 v[34:37], v[34:35], off
	s_nop 0
	global_load_dwordx4 v[38:41], v38, s[54:55]
	s_nop 0
	global_load_dwordx4 v[42:45], v[42:43], off
	s_nop 0
	global_load_dwordx4 v[46:49], v46, s[54:55]
	v_mov_b32_e32 v115, v69
	v_mov_b32_e32 v171, v167
	v_add_u32_e32 v170, 0x11000, v66
	v_add_u32_e32 v170, s9, v170
	s_load_dwordx16 s[52:67], s[0:1], 0x0
	v_and_b32_e32 v178, 63, v171
	v_ashrrev_i32_e32 v171, 31, v170
	v_cmp_lt_i32_e32 vcc, v94, v93
	v_lshlrev_b64 v[172:173], 13, v[170:171]
	s_load_dwordx16 s[36:51], s[0:1], 0x80
	v_cndmask_b32_e32 v171, v92, v94, vcc
	v_cmp_lt_i32_e32 vcc, v95, v93
	v_lshlrev_b32_e32 v148, 2, v171
	v_lshlrev_b32_e32 v114, 4, v178
	v_cndmask_b32_e32 v171, v92, v95, vcc
	v_cmp_lt_i32_e32 vcc, v96, v93
	v_lshlrev_b32_e32 v139, 2, v171
	s_waitcnt lgkmcnt(0)
	v_lshl_add_u64 v[172:173], s[52:53], 0, v[172:173]
	v_cndmask_b32_e32 v171, v92, v96, vcc
	v_cmp_lt_i32_e32 vcc, v97, v93
	v_lshlrev_b32_e32 v138, 2, v171
	v_or_b32_e32 v206, 0x1000, v114
	v_cndmask_b32_e32 v171, v92, v97, vcc
	v_cmp_lt_i32_e32 vcc, v98, v93
	v_mov_b32_e32 v207, v115
	v_or_b32_e32 v214, 0x1400, v114
	v_mov_b32_e32 v215, v115
	v_or_b32_e32 v222, 0x1800, v114
	v_mov_b32_e32 v223, v115
	v_or_b32_e32 v230, 0x1c00, v114
	v_mov_b32_e32 v231, v115
	v_lshlrev_b32_e32 v137, 2, v171
	v_cndmask_b32_e32 v171, v92, v98, vcc
	v_cmp_lt_i32_e32 vcc, v99, v93
	v_lshl_add_u64 v[194:195], v[172:173], 0, v[114:115]
	v_lshl_add_u64 v[202:203], v[172:173], 0, v[206:207]
	v_lshl_add_u64 v[210:211], v[172:173], 0, v[214:215]
	v_lshl_add_u64 v[218:219], v[172:173], 0, v[222:223]
	v_lshl_add_u64 v[226:227], v[172:173], 0, v[230:231]
	v_lshlrev_b32_e32 v136, 2, v171
	v_cndmask_b32_e32 v171, v92, v99, vcc
	v_mov_b64_e32 v[172:173], s[42:43]
	v_lshlrev_b32_e32 v113, 2, v171
	v_mad_i64_i32 v[170:171], s[4:5], v170, s16, v[172:173]
	v_lshlrev_b32_e32 v172, 3, v178
	v_mov_b32_e32 v173, v115
	global_load_dwordx4 v[174:177], v[194:195], off
	global_load_dwordx4 v[190:193], v[194:195], off offset:1024
	global_load_dwordx4 v[182:185], v114, s[54:55]
	global_load_dwordx4 v[186:189], v114, s[54:55] offset:1024
	v_lshl_add_u64 v[116:117], v[170:171], 0, v[172:173]
	global_load_dwordx4 v[170:173], v[194:195], off offset:2048
	global_load_dwordx4 v[178:181], v114, s[54:55] offset:2048
	global_load_dwordx4 v[198:201], v114, s[54:55] offset:3072
	s_mov_b32 s4, 0x800000
	global_load_dwordx4 v[194:197], v[194:195], off offset:3072
	s_nop 0
	global_load_dwordx4 v[202:205], v[202:203], off
	s_nop 0
	global_load_dwordx4 v[206:209], v206, s[54:55]
	s_nop 0
	global_load_dwordx4 v[210:213], v[210:211], off
	s_nop 0
	global_load_dwordx4 v[214:217], v214, s[54:55]
	s_waitcnt vmcnt(23)
	v_pk_mul_f32 v[74:75], v[6:7], v[6:7]
	s_waitcnt vmcnt(22)
	v_pk_mul_f32 v[86:87], v[22:23], v[22:23]
	v_pk_mul_f32 v[72:73], v[8:9], v[8:9]
	v_pk_mul_f32 v[82:83], v[24:25], v[24:25]
	v_add_f32_e32 v68, v86, v87
	v_add_f32_e32 v74, v74, v75
	v_add_f32_e32 v68, v68, v82
	s_waitcnt vmcnt(15)
	v_mov_b32_e32 v64, v35
	v_mov_b32_e32 v60, v34
	s_waitcnt vmcnt(13)
; __device__ void rms_row(const float* __restrict__ src, const float* __restrict__ gain, u16* __restrict__ dst, int row) {
;     ...
;   for (int i = 0; i < 8; ++i) {
;     v[i] = s4[i * 64 + lane];
;     ss += v[i].x * v[i].x + v[i].y * v[i].y + v[i].z * v[i].z + v[i].w * v[i].w;
;   }
;   ss = wave_sum(ss);
;   const float inv = rsqrtf(ss * (1.f / DM) + 1e-6f);
;   const float4* g4 = (const float4*)gain;
;   uint2* d2 = (uint2*)(dst + (size_t)row * LDK);
; #pragma unroll
;   for (int i = 0; i < 8; ++i) {
;     float4 g = g4[i * 64 + lane];
;     uint2 o;
;     o.x = pack2(v[i].x * inv * g.x, v[i].y * inv * g.y);
;     o.y = pack2(v[i].z * inv * g.z, v[i].w * inv * g.w);
;     d2[i * 64 + lane] = o;
;   }
	v_mov_b32_e32 v65, v43
	v_mov_b32_e32 v61, v42
	v_pk_mul_f32 v[64:65], v[64:65], v[64:65]
	v_mov_b32_e32 v52, v36
	v_mov_b32_e32 v53, v44
	v_pk_fma_f32 v[60:61], v[60:61], v[60:61], v[64:65]
	v_mov_b32_e32 v56, v37
	v_mov_b32_e32 v57, v45
	v_pk_fma_f32 v[52:53], v[52:53], v[52:53], v[60:61]
	v_add_f32_e32 v72, v74, v72
	v_pk_fma_f32 v[78:79], v[56:57], v[56:57], v[52:53]
	global_load_dwordx4 v[50:53], v[50:51], off
	s_nop 0
	global_load_dwordx4 v[54:57], v54, s[54:55]
	s_nop 0
	global_load_dwordx4 v[58:61], v[58:59], off
	s_nop 0
	global_load_dwordx4 v[62:65], v62, s[54:55]
	v_pk_mul_f32 v[84:85], v[2:3], v[2:3]
	v_add_f32_e32 v68, v68, v83
	v_add_f32_e32 v72, v72, v73
	v_pk_mul_f32 v[80:81], v[4:5], v[4:5]
	v_add_f32_e32 v68, v72, v68
	v_add_f32_e32 v72, v84, v85
	v_add_f32_e32 v72, v72, v80
	v_pk_mul_f32 v[88:89], v[26:27], v[26:27]
	v_add_f32_e32 v72, v72, v81
	v_pk_mul_f32 v[76:77], v[28:29], v[28:29]
	v_add_f32_e32 v68, v68, v72
	v_add_f32_e32 v72, v88, v89
	v_add_f32_e32 v72, v72, v76
	v_add_f32_e32 v72, v72, v77
	v_add_f32_e32 v68, v68, v72
	v_add_f32_e32 v68, v68, v78
	v_add_f32_e32 v68, v68, v79
	s_waitcnt vmcnt(3)
	v_mov_b32_e32 v110, v51
	v_mov_b32_e32 v108, v50
	s_waitcnt vmcnt(1)
	v_mov_b32_e32 v111, v59
	v_mov_b32_e32 v109, v58
	v_pk_mul_f32 v[110:111], v[110:111], v[110:111]
	v_mov_b32_e32 v104, v52
	v_mov_b32_e32 v105, v60
	v_pk_fma_f32 v[108:109], v[108:109], v[108:109], v[110:111]
	v_mov_b32_e32 v106, v53
	v_mov_b32_e32 v107, v61
	v_pk_fma_f32 v[104:105], v[104:105], v[104:105], v[108:109]
	s_nop 0
	v_pk_fma_f32 v[104:105], v[106:107], v[106:107], v[104:105]
	s_nop 0
	v_add_f32_e32 v68, v68, v104
	v_add_f32_e32 v68, v68, v105
	ds_bpermute_b32 v72, v112, v68
	s_waitcnt lgkmcnt(0)
	v_add_f32_e32 v68, v68, v72
	ds_bpermute_b32 v72, v103, v68
	s_waitcnt lgkmcnt(0)
	v_add_f32_e32 v68, v68, v72
	ds_bpermute_b32 v72, v102, v68
	s_waitcnt lgkmcnt(0)
	v_add_f32_e32 v68, v68, v72
	ds_bpermute_b32 v72, v101, v68
	s_waitcnt lgkmcnt(0)
	v_add_f32_e32 v68, v68, v72
	ds_bpermute_b32 v72, v100, v68
	s_waitcnt lgkmcnt(0)
	v_add_f32_e32 v68, v68, v72
	ds_bpermute_b32 v67, v67, v68
	s_waitcnt lgkmcnt(0)
	v_add_f32_e32 v67, v68, v67
	v_fmamk_f32 v67, v67, 0x3a000000, v91
	v_cmp_gt_f32_e32 vcc, s4, v67
	v_mul_f32_e32 v68, 0x4b800000, v67
	s_nop 0
	v_cndmask_b32_e32 v67, v67, v68, vcc
	v_rsq_f32_e32 v67, v67
	s_nop 0
	v_mul_f32_e32 v68, 0x45800000, v67
	v_cndmask_b32_e32 v68, v67, v68, vcc
	v_pk_mul_f32 v[2:3], v[2:3], v[68:69] op_sel_hi:[1,0]
	v_pk_mul_f32 v[4:5], v[4:5], v[68:69] op_sel_hi:[1,0]
	v_pk_mul_f32 v[2:3], v[2:3], v[10:11]
	v_pk_mul_f32 v[4:5], v[4:5], v[12:13]
	v_cvt_pk_bf16_f32 v2, v2, v3
	v_cvt_pk_bf16_f32 v3, v4, v5
	global_store_dwordx2 v[70:71], v[2:3], off offset:1024
	v_pk_mul_f32 v[2:3], v[26:27], v[68:69] op_sel_hi:[1,0]
	v_pk_mul_f32 v[4:5], v[28:29], v[68:69] op_sel_hi:[1,0]
	v_pk_mul_f32 v[2:3], v[2:3], v[30:31]
	v_pk_mul_f32 v[4:5], v[4:5], v[32:33]
	v_cvt_pk_bf16_f32 v2, v2, v3
	v_cvt_pk_bf16_f32 v3, v4, v5
	global_store_dwordx2 v[70:71], v[2:3], off offset:1536
	v_pk_mul_f32 v[2:3], v[34:35], v[68:69] op_sel_hi:[1,0]
	v_pk_mul_f32 v[4:5], v[36:37], v[68:69] op_sel_hi:[1,0]
	v_pk_mul_f32 v[2:3], v[2:3], v[38:39]
	v_pk_mul_f32 v[4:5], v[4:5], v[40:41]
	v_cvt_pk_bf16_f32 v2, v2, v3
	v_cvt_pk_bf16_f32 v3, v4, v5
	global_store_dwordx2 v[70:71], v[2:3], off offset:2048
	v_pk_mul_f32 v[2:3], v[42:43], v[68:69] op_sel_hi:[1,0]
	v_pk_mul_f32 v[4:5], v[44:45], v[68:69] op_sel_hi:[1,0]
	v_pk_mul_f32 v[2:3], v[2:3], v[46:47]
	v_pk_mul_f32 v[4:5], v[4:5], v[48:49]
	v_cvt_pk_bf16_f32 v2, v2, v3
	v_cvt_pk_bf16_f32 v3, v4, v5
	v_pk_mul_f32 v[6:7], v[6:7], v[68:69] op_sel_hi:[1,0]
	v_pk_mul_f32 v[8:9], v[8:9], v[68:69] op_sel_hi:[1,0]
	global_store_dwordx2 v[70:71], v[2:3], off offset:2560
	v_pk_mul_f32 v[2:3], v[50:51], v[68:69] op_sel_hi:[1,0]
	v_pk_mul_f32 v[4:5], v[52:53], v[68:69] op_sel_hi:[1,0]
	v_pk_mul_f32 v[6:7], v[14:15], v[6:7]
	v_pk_mul_f32 v[8:9], v[16:17], v[8:9]
	v_pk_mul_f32 v[2:3], v[2:3], v[54:55]
	v_pk_mul_f32 v[4:5], v[4:5], v[56:57]
	v_cvt_pk_bf16_f32 v6, v6, v7
	v_cvt_pk_bf16_f32 v7, v8, v9
	v_cvt_pk_bf16_f32 v2, v2, v3
	v_cvt_pk_bf16_f32 v3, v4, v5
	global_store_dwordx2 v[70:71], v[6:7], off
	v_pk_mul_f32 v[6:7], v[22:23], v[68:69] op_sel_hi:[1,0]
	v_pk_mul_f32 v[8:9], v[24:25], v[68:69] op_sel_hi:[1,0]
	global_store_dwordx2 v[70:71], v[2:3], off offset:3072
	v_pk_mul_f32 v[2:3], v[58:59], v[68:69] op_sel_hi:[1,0]
	v_pk_mul_f32 v[4:5], v[60:61], v[68:69] op_sel_hi:[1,0]
	v_pk_mul_f32 v[6:7], v[18:19], v[6:7]
	v_pk_mul_f32 v[8:9], v[20:21], v[8:9]
	s_waitcnt vmcnt(6)
	v_pk_mul_f32 v[2:3], v[2:3], v[62:63]
	v_pk_mul_f32 v[4:5], v[4:5], v[64:65]
	v_cvt_pk_bf16_f32 v6, v6, v7
	v_cvt_pk_bf16_f32 v7, v8, v9
	v_cvt_pk_bf16_f32 v2, v2, v3
	v_cvt_pk_bf16_f32 v3, v4, v5
	global_store_dwordx2 v[70:71], v[6:7], off offset:512
	global_store_dwordx2 v[70:71], v[2:3], off offset:3584
	s_waitcnt vmcnt(23)
	v_pk_mul_f32 v[120:121], v[174:175], v[174:175]
	s_waitcnt vmcnt(22)
	v_pk_mul_f32 v[132:133], v[190:191], v[190:191]
	v_pk_mul_f32 v[118:119], v[176:177], v[176:177]
	v_pk_mul_f32 v[128:129], v[192:193], v[192:193]
	v_add_f32_e32 v114, v132, v133
	v_add_f32_e32 v120, v120, v121
	v_add_f32_e32 v114, v114, v128
	s_waitcnt vmcnt(15)
	v_mov_b32_e32 v232, v203
	v_mov_b32_e32 v228, v202
	s_waitcnt vmcnt(13)
; __device__ void rms_row(const float* __restrict__ src, const float* __restrict__ gain, u16* __restrict__ dst, int row) {
;     ...
;   for (int i = 0; i < 8; ++i) {
;     v[i] = s4[i * 64 + lane];
;     ss += v[i].x * v[i].x + v[i].y * v[i].y + v[i].z * v[i].z + v[i].w * v[i].w;
;   }
;   ss = wave_sum(ss);
;   const float inv = rsqrtf(ss * (1.f / DM) + 1e-6f);
;   const float4* g4 = (const float4*)gain;
;   uint2* d2 = (uint2*)(dst + (size_t)row * LDK);
; #pragma unroll
;   for (int i = 0; i < 8; ++i) {
;     float4 g = g4[i * 64 + lane];
;     uint2 o;
;     o.x = pack2(v[i].x * inv * g.x, v[i].y * inv * g.y);
;     o.y = pack2(v[i].z * inv * g.z, v[i].w * inv * g.w);
;     d2[i * 64 + lane] = o;
;   }
	v_mov_b32_e32 v233, v211
	v_mov_b32_e32 v229, v210
	v_pk_mul_f32 v[232:233], v[232:233], v[232:233]
	v_mov_b32_e32 v220, v204
	v_mov_b32_e32 v221, v212
	v_pk_fma_f32 v[228:229], v[228:229], v[228:229], v[232:233]
	v_mov_b32_e32 v224, v205
	v_mov_b32_e32 v225, v213
	v_pk_fma_f32 v[220:221], v[220:221], v[220:221], v[228:229]
	v_add_f32_e32 v118, v120, v118
	v_pk_fma_f32 v[124:125], v[224:225], v[224:225], v[220:221]
	global_load_dwordx4 v[218:221], v[218:219], off
	s_nop 0
	global_load_dwordx4 v[222:225], v222, s[54:55]
	s_nop 0
	global_load_dwordx4 v[226:229], v[226:227], off
	s_nop 0
	global_load_dwordx4 v[230:233], v230, s[54:55]
	v_pk_mul_f32 v[130:131], v[170:171], v[170:171]
	v_add_f32_e32 v114, v114, v129
	v_add_f32_e32 v118, v118, v119
	v_pk_mul_f32 v[126:127], v[172:173], v[172:173]
	v_add_f32_e32 v114, v118, v114
	v_add_f32_e32 v118, v130, v131
	v_add_f32_e32 v118, v118, v126
	v_pk_mul_f32 v[134:135], v[194:195], v[194:195]
	v_add_f32_e32 v118, v118, v127
	v_pk_mul_f32 v[122:123], v[196:197], v[196:197]
	v_add_f32_e32 v114, v114, v118
	v_add_f32_e32 v118, v134, v135
	v_add_f32_e32 v118, v118, v122
	v_add_f32_e32 v118, v118, v123
	v_add_f32_e32 v114, v114, v118
	v_add_f32_e32 v114, v114, v124
	v_add_f32_e32 v114, v114, v125
	s_waitcnt vmcnt(3)
	v_mov_b32_e32 v146, v219
	v_mov_b32_e32 v144, v218
	s_waitcnt vmcnt(1)
	v_mov_b32_e32 v147, v227
	v_mov_b32_e32 v145, v226
	v_pk_mul_f32 v[146:147], v[146:147], v[146:147]
	v_mov_b32_e32 v140, v220
	v_mov_b32_e32 v141, v228
	v_pk_fma_f32 v[144:145], v[144:145], v[144:145], v[146:147]
	v_mov_b32_e32 v142, v221
	v_mov_b32_e32 v143, v229
	v_pk_fma_f32 v[140:141], v[140:141], v[140:141], v[144:145]
	s_nop 0
	v_pk_fma_f32 v[140:141], v[142:143], v[142:143], v[140:141]
	s_nop 0
	v_add_f32_e32 v114, v114, v140
	v_add_f32_e32 v114, v114, v141
	ds_bpermute_b32 v118, v148, v114
	s_waitcnt lgkmcnt(0)
	v_add_f32_e32 v114, v114, v118
	ds_bpermute_b32 v118, v139, v114
	s_waitcnt lgkmcnt(0)
	v_add_f32_e32 v114, v114, v118
	ds_bpermute_b32 v118, v138, v114
	s_waitcnt lgkmcnt(0)
	v_add_f32_e32 v114, v114, v118
	ds_bpermute_b32 v118, v137, v114
	s_waitcnt lgkmcnt(0)
	v_add_f32_e32 v114, v114, v118
	ds_bpermute_b32 v118, v136, v114
	s_waitcnt lgkmcnt(0)
	v_add_f32_e32 v114, v114, v118
	ds_bpermute_b32 v113, v113, v114
	s_waitcnt lgkmcnt(0)
	v_add_f32_e32 v113, v114, v113
	v_fmamk_f32 v113, v113, 0x3a000000, v91
	v_cmp_gt_f32_e32 vcc, s4, v113
	v_mul_f32_e32 v114, 0x4b800000, v113
	s_nop 0
	v_cndmask_b32_e32 v113, v113, v114, vcc
	v_rsq_f32_e32 v113, v113
	s_nop 0
	v_mul_f32_e32 v114, 0x45800000, v113
	v_cndmask_b32_e32 v114, v113, v114, vcc
	v_pk_mul_f32 v[170:171], v[170:171], v[114:115] op_sel_hi:[1,0]
	v_pk_mul_f32 v[172:173], v[172:173], v[114:115] op_sel_hi:[1,0]
	v_pk_mul_f32 v[170:171], v[170:171], v[178:179]
	v_pk_mul_f32 v[172:173], v[172:173], v[180:181]
	v_cvt_pk_bf16_f32 v170, v170, v171
	v_cvt_pk_bf16_f32 v171, v172, v173
	global_store_dwordx2 v[116:117], v[170:171], off offset:1024
	v_pk_mul_f32 v[170:171], v[194:195], v[114:115] op_sel_hi:[1,0]
	v_pk_mul_f32 v[172:173], v[196:197], v[114:115] op_sel_hi:[1,0]
	v_pk_mul_f32 v[170:171], v[170:171], v[198:199]
	v_pk_mul_f32 v[172:173], v[172:173], v[200:201]
	v_cvt_pk_bf16_f32 v170, v170, v171
	v_cvt_pk_bf16_f32 v171, v172, v173
	global_store_dwordx2 v[116:117], v[170:171], off offset:1536
	v_pk_mul_f32 v[170:171], v[202:203], v[114:115] op_sel_hi:[1,0]
	v_pk_mul_f32 v[172:173], v[204:205], v[114:115] op_sel_hi:[1,0]
	v_pk_mul_f32 v[170:171], v[170:171], v[206:207]
	v_pk_mul_f32 v[172:173], v[172:173], v[208:209]
	v_cvt_pk_bf16_f32 v170, v170, v171
	v_cvt_pk_bf16_f32 v171, v172, v173
	global_store_dwordx2 v[116:117], v[170:171], off offset:2048
	v_pk_mul_f32 v[170:171], v[210:211], v[114:115] op_sel_hi:[1,0]
	v_pk_mul_f32 v[172:173], v[212:213], v[114:115] op_sel_hi:[1,0]
	v_pk_mul_f32 v[170:171], v[170:171], v[214:215]
	v_pk_mul_f32 v[172:173], v[172:173], v[216:217]
	v_cvt_pk_bf16_f32 v170, v170, v171
	v_cvt_pk_bf16_f32 v171, v172, v173
	v_pk_mul_f32 v[174:175], v[174:175], v[114:115] op_sel_hi:[1,0]
	v_pk_mul_f32 v[176:177], v[176:177], v[114:115] op_sel_hi:[1,0]
	global_store_dwordx2 v[116:117], v[170:171], off offset:2560
	v_pk_mul_f32 v[170:171], v[218:219], v[114:115] op_sel_hi:[1,0]
	v_pk_mul_f32 v[172:173], v[220:221], v[114:115] op_sel_hi:[1,0]
	v_pk_mul_f32 v[174:175], v[182:183], v[174:175]
	v_pk_mul_f32 v[176:177], v[184:185], v[176:177]
	v_pk_mul_f32 v[170:171], v[170:171], v[222:223]
	v_pk_mul_f32 v[172:173], v[172:173], v[224:225]
	v_cvt_pk_bf16_f32 v174, v174, v175
	v_cvt_pk_bf16_f32 v175, v176, v177
	v_cvt_pk_bf16_f32 v170, v170, v171
	v_cvt_pk_bf16_f32 v171, v172, v173
	global_store_dwordx2 v[116:117], v[174:175], off
	v_pk_mul_f32 v[174:175], v[190:191], v[114:115] op_sel_hi:[1,0]
	v_pk_mul_f32 v[176:177], v[192:193], v[114:115] op_sel_hi:[1,0]
	global_store_dwordx2 v[116:117], v[170:171], off offset:3072
	v_pk_mul_f32 v[170:171], v[226:227], v[114:115] op_sel_hi:[1,0]
	v_pk_mul_f32 v[172:173], v[228:229], v[114:115] op_sel_hi:[1,0]
	v_pk_mul_f32 v[174:175], v[186:187], v[174:175]
	v_pk_mul_f32 v[176:177], v[188:189], v[176:177]
	s_waitcnt vmcnt(6)
	v_pk_mul_f32 v[170:171], v[170:171], v[230:231]
	v_pk_mul_f32 v[172:173], v[172:173], v[232:233]
	v_cvt_pk_bf16_f32 v174, v174, v175
	v_cvt_pk_bf16_f32 v175, v176, v177
	v_cvt_pk_bf16_f32 v170, v170, v171
	v_cvt_pk_bf16_f32 v171, v172, v173
	global_store_dwordx2 v[116:117], v[174:175], off offset:512
	global_store_dwordx2 v[116:117], v[170:171], off offset:3584
	s_branch .LBB0_7
; __device__ __forceinline__ int tid_op() { int t = threadIdx.x & 255; asm volatile("" : "+v"(t)); return t; }
; __device__ void rms_row(const float* __restrict__ src, const float* __restrict__ gain, u16* __restrict__ dst, int row) {
;   const int lane = tid_op() & 63;
;   const float4* s4 = (const float4*)(src + (size_t)row * DM);
;   float4 v[8];
;   float ss = 0.f;
; #pragma unroll
;   for (int i = 0; i < 8; ++i) {
;     v[i] = s4[i * 64 + lane];
;     ss += v[i].x * v[i].x + v[i].y * v[i].y + v[i].z * v[i].z + v[i].w * v[i].w;
;   }
.Lrms_single:
	v_mov_b32_e32 v3, v167
	v_add_u32_e32 v2, 0x11000, v66
	s_load_dwordx16 s[52:67], s[0:1], 0x0
	v_and_b32_e32 v10, 63, v3
	v_ashrrev_i32_e32 v3, 31, v2
	v_cmp_lt_i32_e32 vcc, v94, v93
	v_lshlrev_b64 v[4:5], 13, v[2:3]
	s_load_dwordx16 s[36:51], s[0:1], 0x80
	v_cndmask_b32_e32 v3, v92, v94, vcc
	v_cmp_lt_i32_e32 vcc, v95, v93
	v_lshlrev_b32_e32 v112, 2, v3
	v_lshlrev_b32_e32 v68, 4, v10
	v_cndmask_b32_e32 v3, v92, v95, vcc
	v_cmp_lt_i32_e32 vcc, v96, v93
	v_lshlrev_b32_e32 v103, 2, v3
	s_waitcnt lgkmcnt(0)
	v_lshl_add_u64 v[4:5], s[52:53], 0, v[4:5]
	v_cndmask_b32_e32 v3, v92, v96, vcc
	v_cmp_lt_i32_e32 vcc, v97, v93
	v_lshlrev_b32_e32 v102, 2, v3
	v_or_b32_e32 v38, 0x1000, v68
	v_cndmask_b32_e32 v3, v92, v97, vcc
	v_cmp_lt_i32_e32 vcc, v98, v93
	v_mov_b32_e32 v39, v69
	v_or_b32_e32 v46, 0x1400, v68
	v_mov_b32_e32 v47, v69
	v_or_b32_e32 v54, 0x1800, v68
	v_mov_b32_e32 v55, v69
	v_or_b32_e32 v62, 0x1c00, v68
	v_mov_b32_e32 v63, v69
	v_lshlrev_b32_e32 v101, 2, v3
	v_cndmask_b32_e32 v3, v92, v98, vcc
	v_cmp_lt_i32_e32 vcc, v99, v93
	v_lshl_add_u64 v[26:27], v[4:5], 0, v[68:69]
	v_lshl_add_u64 v[34:35], v[4:5], 0, v[38:39]
	v_lshl_add_u64 v[42:43], v[4:5], 0, v[46:47]
	v_lshl_add_u64 v[50:51], v[4:5], 0, v[54:55]
	v_lshl_add_u64 v[58:59], v[4:5], 0, v[62:63]
	v_lshlrev_b32_e32 v100, 2, v3
	v_cndmask_b32_e32 v3, v92, v99, vcc
	v_mov_b64_e32 v[4:5], s[42:43]
	v_lshlrev_b32_e32 v67, 2, v3
	v_mad_i64_i32 v[2:3], s[4:5], v2, s16, v[4:5]
	v_lshlrev_b32_e32 v4, 3, v10
	v_mov_b32_e32 v5, v69
	global_load_dwordx4 v[6:9], v[26:27], off
	global_load_dwordx4 v[22:25], v[26:27], off offset:1024
	global_load_dwordx4 v[14:17], v68, s[54:55]
	global_load_dwordx4 v[18:21], v68, s[54:55] offset:1024
	v_lshl_add_u64 v[70:71], v[2:3], 0, v[4:5]
	global_load_dwordx4 v[2:5], v[26:27], off offset:2048
	global_load_dwordx4 v[10:13], v68, s[54:55] offset:2048
	global_load_dwordx4 v[30:33], v68, s[54:55] offset:3072
	s_mov_b32 s4, 0x800000
	global_load_dwordx4 v[26:29], v[26:27], off offset:3072
	s_nop 0
	global_load_dwordx4 v[34:37], v[34:35], off
	s_nop 0
	global_load_dwordx4 v[38:41], v38, s[54:55]
	s_nop 0
	global_load_dwordx4 v[42:45], v[42:43], off
	s_nop 0
	global_load_dwordx4 v[46:49], v46, s[54:55]
	s_waitcnt vmcnt(11)
	v_pk_mul_f32 v[74:75], v[6:7], v[6:7]
	s_waitcnt vmcnt(10)
	v_pk_mul_f32 v[86:87], v[22:23], v[22:23]
	v_pk_mul_f32 v[72:73], v[8:9], v[8:9]
	v_pk_mul_f32 v[82:83], v[24:25], v[24:25]
	v_add_f32_e32 v68, v86, v87
	v_add_f32_e32 v74, v74, v75
	v_add_f32_e32 v68, v68, v82
	s_waitcnt vmcnt(3)
	v_mov_b32_e32 v64, v35
	v_mov_b32_e32 v60, v34
	s_waitcnt vmcnt(1)
	v_mov_b32_e32 v65, v43
	v_mov_b32_e32 v61, v42
	v_pk_mul_f32 v[64:65], v[64:65], v[64:65]
	v_mov_b32_e32 v52, v36
	v_mov_b32_e32 v53, v44
	v_pk_fma_f32 v[60:61], v[60:61], v[60:61], v[64:65]
	v_mov_b32_e32 v56, v37
	v_mov_b32_e32 v57, v45
	v_pk_fma_f32 v[52:53], v[52:53], v[52:53], v[60:61]
	v_add_f32_e32 v72, v74, v72
	v_pk_fma_f32 v[78:79], v[56:57], v[56:57], v[52:53]
	global_load_dwordx4 v[50:53], v[50:51], off
	s_nop 0
	global_load_dwordx4 v[54:57], v54, s[54:55]
	s_nop 0
	global_load_dwordx4 v[58:61], v[58:59], off
	s_nop 0
	global_load_dwordx4 v[62:65], v62, s[54:55]
	v_pk_mul_f32 v[84:85], v[2:3], v[2:3]
	v_add_f32_e32 v68, v68, v83
	v_add_f32_e32 v72, v72, v73
	v_pk_mul_f32 v[80:81], v[4:5], v[4:5]
	v_add_f32_e32 v68, v72, v68
	v_add_f32_e32 v72, v84, v85
	v_add_f32_e32 v72, v72, v80
	v_pk_mul_f32 v[88:89], v[26:27], v[26:27]
	v_add_f32_e32 v72, v72, v81
	v_pk_mul_f32 v[76:77], v[28:29], v[28:29]
	v_add_f32_e32 v68, v68, v72
	v_add_f32_e32 v72, v88, v89
	v_add_f32_e32 v72, v72, v76
	v_add_f32_e32 v72, v72, v77
	v_add_f32_e32 v68, v68, v72
	v_add_f32_e32 v68, v68, v78
	v_add_f32_e32 v68, v68, v79
	s_waitcnt vmcnt(3)
; __device__ void rms_row(const float* __restrict__ src, const float* __restrict__ gain, u16* __restrict__ dst, int row) {
;     ...
;   ss = wave_sum(ss);
;   const float inv = rsqrtf(ss * (1.f / DM) + 1e-6f);
;   const float4* g4 = (const float4*)gain;
;   uint2* d2 = (uint2*)(dst + (size_t)row * LDK);
; #pragma unroll
;   for (int i = 0; i < 8; ++i) {
;     float4 g = g4[i * 64 + lane];
;     uint2 o;
;     o.x = pack2(v[i].x * inv * g.x, v[i].y * inv * g.y);
;     o.y = pack2(v[i].z * inv * g.z, v[i].w * inv * g.w);
;     d2[i * 64 + lane] = o;
;   }
	v_mov_b32_e32 v110, v51
	v_mov_b32_e32 v108, v50
	s_waitcnt vmcnt(1)
	v_mov_b32_e32 v111, v59
	v_mov_b32_e32 v109, v58
	v_pk_mul_f32 v[110:111], v[110:111], v[110:111]
	v_mov_b32_e32 v104, v52
	v_mov_b32_e32 v105, v60
	v_pk_fma_f32 v[108:109], v[108:109], v[108:109], v[110:111]
	v_mov_b32_e32 v106, v53
	v_mov_b32_e32 v107, v61
	v_pk_fma_f32 v[104:105], v[104:105], v[104:105], v[108:109]
	s_nop 0
	v_pk_fma_f32 v[104:105], v[106:107], v[106:107], v[104:105]
	s_nop 0
	v_add_f32_e32 v68, v68, v104
	v_add_f32_e32 v68, v68, v105
	ds_bpermute_b32 v72, v112, v68
	s_waitcnt lgkmcnt(0)
	v_add_f32_e32 v68, v68, v72
	ds_bpermute_b32 v72, v103, v68
	s_waitcnt lgkmcnt(0)
	v_add_f32_e32 v68, v68, v72
	ds_bpermute_b32 v72, v102, v68
	s_waitcnt lgkmcnt(0)
	v_add_f32_e32 v68, v68, v72
	ds_bpermute_b32 v72, v101, v68
	s_waitcnt lgkmcnt(0)
	v_add_f32_e32 v68, v68, v72
	ds_bpermute_b32 v72, v100, v68
	s_waitcnt lgkmcnt(0)
	v_add_f32_e32 v68, v68, v72
	ds_bpermute_b32 v67, v67, v68
	s_waitcnt lgkmcnt(0)
	v_add_f32_e32 v67, v68, v67
	v_fmamk_f32 v67, v67, 0x3a000000, v91
	v_cmp_gt_f32_e32 vcc, s4, v67
	v_mul_f32_e32 v68, 0x4b800000, v67
	s_nop 0
	v_cndmask_b32_e32 v67, v67, v68, vcc
	v_rsq_f32_e32 v67, v67
	s_nop 0
	v_mul_f32_e32 v68, 0x45800000, v67
	v_cndmask_b32_e32 v68, v67, v68, vcc
	v_pk_mul_f32 v[2:3], v[2:3], v[68:69] op_sel_hi:[1,0]
	v_pk_mul_f32 v[4:5], v[4:5], v[68:69] op_sel_hi:[1,0]
	v_pk_mul_f32 v[2:3], v[2:3], v[10:11]
	v_pk_mul_f32 v[4:5], v[4:5], v[12:13]
	v_cvt_pk_bf16_f32 v2, v2, v3
	v_cvt_pk_bf16_f32 v3, v4, v5
	global_store_dwordx2 v[70:71], v[2:3], off offset:1024
	v_pk_mul_f32 v[2:3], v[26:27], v[68:69] op_sel_hi:[1,0]
	v_pk_mul_f32 v[4:5], v[28:29], v[68:69] op_sel_hi:[1,0]
	v_pk_mul_f32 v[2:3], v[2:3], v[30:31]
	v_pk_mul_f32 v[4:5], v[4:5], v[32:33]
	v_cvt_pk_bf16_f32 v2, v2, v3
	v_cvt_pk_bf16_f32 v3, v4, v5
	global_store_dwordx2 v[70:71], v[2:3], off offset:1536
	v_pk_mul_f32 v[2:3], v[34:35], v[68:69] op_sel_hi:[1,0]
	v_pk_mul_f32 v[4:5], v[36:37], v[68:69] op_sel_hi:[1,0]
	v_pk_mul_f32 v[2:3], v[2:3], v[38:39]
	v_pk_mul_f32 v[4:5], v[4:5], v[40:41]
	v_cvt_pk_bf16_f32 v2, v2, v3
	v_cvt_pk_bf16_f32 v3, v4, v5
	global_store_dwordx2 v[70:71], v[2:3], off offset:2048
	v_pk_mul_f32 v[2:3], v[42:43], v[68:69] op_sel_hi:[1,0]
	v_pk_mul_f32 v[4:5], v[44:45], v[68:69] op_sel_hi:[1,0]
	v_pk_mul_f32 v[2:3], v[2:3], v[46:47]
	v_pk_mul_f32 v[4:5], v[4:5], v[48:49]
	v_cvt_pk_bf16_f32 v2, v2, v3
	v_cvt_pk_bf16_f32 v3, v4, v5
	v_pk_mul_f32 v[6:7], v[6:7], v[68:69] op_sel_hi:[1,0]
	v_pk_mul_f32 v[8:9], v[8:9], v[68:69] op_sel_hi:[1,0]
	global_store_dwordx2 v[70:71], v[2:3], off offset:2560
	v_pk_mul_f32 v[2:3], v[50:51], v[68:69] op_sel_hi:[1,0]
	v_pk_mul_f32 v[4:5], v[52:53], v[68:69] op_sel_hi:[1,0]
	v_pk_mul_f32 v[6:7], v[14:15], v[6:7]
	v_pk_mul_f32 v[8:9], v[16:17], v[8:9]
	v_pk_mul_f32 v[2:3], v[2:3], v[54:55]
	v_pk_mul_f32 v[4:5], v[4:5], v[56:57]
	v_cvt_pk_bf16_f32 v6, v6, v7
	v_cvt_pk_bf16_f32 v7, v8, v9
	v_cvt_pk_bf16_f32 v2, v2, v3
	v_cvt_pk_bf16_f32 v3, v4, v5
	global_store_dwordx2 v[70:71], v[6:7], off
	v_pk_mul_f32 v[6:7], v[22:23], v[68:69] op_sel_hi:[1,0]
	v_pk_mul_f32 v[8:9], v[24:25], v[68:69] op_sel_hi:[1,0]
	global_store_dwordx2 v[70:71], v[2:3], off offset:3072
	v_pk_mul_f32 v[2:3], v[58:59], v[68:69] op_sel_hi:[1,0]
	v_pk_mul_f32 v[4:5], v[60:61], v[68:69] op_sel_hi:[1,0]
	v_pk_mul_f32 v[6:7], v[18:19], v[6:7]
	v_pk_mul_f32 v[8:9], v[20:21], v[8:9]
	s_waitcnt vmcnt(6)
	v_pk_mul_f32 v[2:3], v[2:3], v[62:63]
	v_pk_mul_f32 v[4:5], v[4:5], v[64:65]
	v_cvt_pk_bf16_f32 v6, v6, v7
	v_cvt_pk_bf16_f32 v7, v8, v9
	v_cvt_pk_bf16_f32 v2, v2, v3
	v_cvt_pk_bf16_f32 v3, v4, v5
	global_store_dwordx2 v[70:71], v[6:7], off offset:512
	global_store_dwordx2 v[70:71], v[2:3], off offset:3584
	s_branch .LBB0_7
